# P1 head-norm+rope epilogue hand-scheduled (batched row-scale reduction, 3 row groups of table loads in flight) + P5 merge epilogue pipelined + P7 U stores nt
# speedup vs baseline: 1.0078x; 1.0036x over previous
.LBB0_231:
	s_cmp_gt_i32 s7, 1
	s_mov_b64 s[0:1], -1
	s_cbranch_scc0 .LBB0_237
	v_min_i32_e32 v131, 3, v215
	s_lshl_b32 s0, s97, 8
	v_readlane_b32 s1, v253, 62
	v_lshlrev_b32_e32 v132, 2, v131
	s_add_i32 s0, s0, s1
	v_cmp_gt_i32_e32 vcc, 4, v215
	v_cmp_gt_i32_e64 s[4:5], 16, v132
	v_or_b32_e32 v131, 1, v132
	v_add_u32_e32 v217, s0, v216
	s_and_b64 s[0:1], vcc, s[4:5]
	v_cmp_gt_i32_e64 s[4:5], 16, v131
	v_or_b32_e32 v131, 2, v132
	v_cndmask_b32_e64 v161, 0, 1.0, s[0:1]
	s_and_b64 s[0:1], vcc, s[4:5]
	v_cmp_gt_i32_e64 s[4:5], 16, v131
	v_or_b32_e32 v131, 3, v132
	v_and_b32_e32 v134, 64, v209
	v_cndmask_b32_e64 v185, 0, 1.0, s[0:1]
	s_and_b64 s[0:1], vcc, s[4:5]
	v_cmp_gt_i32_e64 s[4:5], 16, v131
	v_xor_b32_e32 v131, 16, v209
	v_add_u32_e32 v134, 64, v134
	v_cndmask_b32_e64 v191, 0, 1.0, s[0:1]
	s_and_b64 s[0:1], vcc, s[4:5]
	v_cmp_lt_i32_e32 vcc, v131, v134
	v_add_u32_e32 v130, s34, v217
	v_ashrrev_i32_e32 v133, 31, v132
	v_cndmask_b32_e32 v131, v209, v131, vcc
	v_lshlrev_b32_e32 v218, 2, v131
	v_xor_b32_e32 v131, 32, v209
	v_cmp_lt_i32_e32 vcc, v131, v134
	v_lshl_add_u64 v[132:133], v[132:133], 2, s[18:19]
	v_cndmask_b32_e64 v193, 0, 1.0, s[0:1]
	v_cndmask_b32_e32 v131, v209, v131, vcc
	v_lshlrev_b32_e32 v159, 2, v131
	v_ashrrev_i32_e32 v131, 31, v130
	v_lshlrev_b64 v[134:135], 6, v[130:131]
	v_lshl_add_u64 v[156:157], v[132:133], 0, v[134:135]
	global_load_dwordx4 v[132:135], v[156:157], off
	global_load_dwordx4 v[136:139], v[156:157], off offset:1024
	global_load_dwordx4 v[140:143], v[156:157], off offset:2048
	global_load_dwordx4 v[162:165], v[156:157], off offset:3072
	v_add_u32_e32 v223, 16, v217
	v_add_u32_e32 v220, 32, v217
	s_mov_b64 s[0:1], -1
	s_andn2_b64 vcc, exec, s[94:95]
	v_mul_lo_u32 v195, s87, v217
	v_ashrrev_i32_e32 v225, 31, v223
	v_mul_lo_u32 v224, s87, v223
	v_ashrrev_i32_e32 v222, 31, v220
	v_mul_lo_u32 v221, s87, v220
	v_add_u32_e32 v219, 48, v217
	s_waitcnt vmcnt(0)
	v_mul_f32_e32 v133, v185, v133
	v_fmac_f32_e32 v133, v161, v132
	v_mul_f32_e32 v132, v193, v135
	v_fmac_f32_e32 v132, v191, v134
	v_add_f32_e32 v227, v133, v132
	v_mul_f32_e32 v132, v185, v137
	v_mul_f32_e32 v133, v193, v139
	v_fmac_f32_e32 v132, v161, v136
	v_fmac_f32_e32 v133, v191, v138
	v_add_f32_e32 v226, v132, v133
	v_mul_f32_e32 v230, v185, v141
	v_mul_f32_e32 v231, v193, v143
	v_mul_f32_e32 v228, v185, v163
	v_mul_f32_e32 v229, v193, v165
	v_ashrrev_i32_e32 v132, 31, v217
	v_fmac_f32_e32 v230, v161, v140
	v_fmac_f32_e32 v231, v191, v142
	v_fmac_f32_e32 v228, v161, v162
	v_fmac_f32_e32 v229, v191, v164
	v_mul_lo_u32 v197, s86, v132
	s_cbranch_vccnz .LBB0_234
	v_lshlrev_b32_e32 v130, 7, v130
	v_lshl_add_u32 v130, v215, 5, v130
	v_lshlrev_b32_e32 v144, 5, v215
	v_mul_lo_u32 v131, v217, s86
	v_add_u32_e32 v131, s84, v131
	v_lshl_add_u32 v131, v215, 3, v131
	v_lshlrev_b32_e32 v131, 1, v131
	v_add_co_u32_e32 v156, vcc, 0x2000, v156
	s_nop 1
	v_addc_co_u32_e32 v157, vcc, 0, v157, vcc
	global_load_dwordx4 v[180:183], v[156:157], off
	global_load_dwordx4 v[184:187], v[156:157], off offset:1024
	global_load_dwordx4 v[188:191], v[156:157], off offset:2048
	global_load_dwordx4 v[192:195], v[156:157], off offset:3072
	global_load_dwordx4 v[132:135], v144, s[92:93]
	global_load_dwordx4 v[136:139], v144, s[92:93] offset:16
	global_load_dwordx4 v[160:163], v144, s[92:93] offset:128
	global_load_dwordx4 v[164:167], v144, s[92:93] offset:144
	s_add_u32 s0, s38, 0x0
	s_addc_u32 s1, s39, 0
	s_add_u32 s2, s44, 0x0
	s_addc_u32 s3, s45, 0
	global_load_dwordx4 v[232:235], v130, s[0:1]
	global_load_dwordx4 v[236:239], v130, s[0:1] offset:16
	global_load_dwordx4 v[240:243], v130, s[2:3]
	global_load_dwordx4 v[244:247], v130, s[2:3] offset:16
	s_add_u32 s0, s38, 0x800
	s_addc_u32 s1, s39, 0
	s_add_u32 s2, s44, 0x800
	s_addc_u32 s3, s45, 0
	global_load_dwordx4 v[248:251], v130, s[0:1]
	global_load_dwordx4 v[196:199], v130, s[0:1] offset:16
	global_load_dwordx4 v[200:203], v130, s[2:3]
	global_load_dwordx4 v[140:143], v130, s[2:3] offset:16
	v_add_f32_e32 v230, v230, v231
	v_add_f32_e32 v228, v228, v229
	ds_bpermute_b32 v222, v218, v227
	ds_bpermute_b32 v223, v218, v226
	ds_bpermute_b32 v224, v218, v230
	ds_bpermute_b32 v225, v218, v228
	s_waitcnt lgkmcnt(0)
	v_add_f32_e32 v227, v227, v222
	v_add_f32_e32 v226, v226, v223
	v_add_f32_e32 v230, v230, v224
	v_add_f32_e32 v228, v228, v225
	ds_bpermute_b32 v222, v159, v227
	ds_bpermute_b32 v223, v159, v226
	ds_bpermute_b32 v224, v159, v230
	ds_bpermute_b32 v225, v159, v228
	s_waitcnt lgkmcnt(0)
	v_add_f32_e32 v227, v227, v222
	v_add_f32_e32 v226, v226, v223
	v_add_f32_e32 v230, v230, v224
	v_add_f32_e32 v228, v228, v225
	v_fmamk_f32 v227, v227, 0x3a800000, v207
	v_fmamk_f32 v226, v226, 0x3a800000, v207
	v_fmamk_f32 v230, v230, 0x3a800000, v207
	v_fmamk_f32 v228, v228, 0x3a800000, v207
	v_rsq_f32_e32 v168, v227
	v_rsq_f32_e32 v169, v226
	v_rsq_f32_e32 v170, v230
	v_rsq_f32_e32 v171, v228
	s_waitcnt vmcnt(12)
	v_add_f32_e32 v180, v180, v181
	v_add_f32_e32 v182, v182, v183
	v_add_f32_e32 v184, v184, v185
	v_add_f32_e32 v186, v186, v187
	v_add_f32_e32 v188, v188, v189
	v_add_f32_e32 v190, v190, v191
	v_add_f32_e32 v192, v192, v193
	v_add_f32_e32 v194, v194, v195
	v_add_f32_e32 v180, v180, v182
	v_add_f32_e32 v184, v184, v186
	v_add_f32_e32 v188, v188, v190
	v_add_f32_e32 v192, v192, v194
	s_nop 0
	ds_bpermute_b32 v222, v218, v180
	ds_bpermute_b32 v223, v218, v184
	ds_bpermute_b32 v224, v218, v188
	ds_bpermute_b32 v225, v218, v192
	s_waitcnt lgkmcnt(0)
	v_add_f32_e32 v180, v180, v222
	v_add_f32_e32 v184, v184, v223
	v_add_f32_e32 v188, v188, v224
	v_add_f32_e32 v192, v192, v225
	s_nop 0
	ds_bpermute_b32 v222, v159, v180
	ds_bpermute_b32 v223, v159, v184
	ds_bpermute_b32 v224, v159, v188
	ds_bpermute_b32 v225, v159, v192
	s_waitcnt lgkmcnt(0)
	v_add_f32_e32 v180, v180, v222
	v_add_f32_e32 v184, v184, v223
	v_add_f32_e32 v188, v188, v224
	v_add_f32_e32 v192, v192, v225
	v_fmamk_f32 v180, v180, 0x3a800000, v207
	v_fmamk_f32 v184, v184, 0x3a800000, v207
	v_fmamk_f32 v188, v188, 0x3a800000, v207
	v_fmamk_f32 v192, v192, 0x3a800000, v207
	v_rsq_f32_e32 v172, v180
	v_rsq_f32_e32 v173, v184
	v_rsq_f32_e32 v174, v188
	v_rsq_f32_e32 v175, v192
	s_nop 0
	s_add_u32 s0, s38, 0x1000
	s_addc_u32 s1, s39, 0
	s_add_u32 s2, s44, 0x1000
	s_addc_u32 s3, s45, 0
	global_load_dwordx4 v[180:183], v130, s[0:1]
	global_load_dwordx4 v[184:187], v130, s[0:1] offset:16
	global_load_dwordx4 v[188:191], v130, s[2:3]
	global_load_dwordx4 v[192:195], v130, s[2:3] offset:16
	s_waitcnt vmcnt(12)
	v_pk_mul_f32 v[132:133], s[6:7], v[132:133] op_sel_hi:[0,1]
	v_pk_mul_f32 v[134:135], s[6:7], v[134:135] op_sel_hi:[0,1]
	v_pk_mul_f32 v[136:137], s[6:7], v[136:137] op_sel_hi:[0,1]
	v_pk_mul_f32 v[138:139], s[6:7], v[138:139] op_sel_hi:[0,1]
	v_pk_mul_f32 v[160:161], s[6:7], v[160:161] op_sel_hi:[0,1]
	v_pk_mul_f32 v[162:163], s[6:7], v[162:163] op_sel_hi:[0,1]
	v_pk_mul_f32 v[164:165], s[6:7], v[164:165] op_sel_hi:[0,1]
	v_pk_mul_f32 v[166:167], s[6:7], v[166:167] op_sel_hi:[0,1]
	v_pk_mul_f32 v[126:127], v[126:127], v[168:169] op_sel_hi:[1,0]
	v_pk_mul_f32 v[118:119], v[118:119], v[168:169] op_sel_hi:[1,0]
	v_pk_mul_f32 v[128:129], v[128:129], v[168:169] op_sel_hi:[1,0]
	v_pk_mul_f32 v[120:121], v[120:121], v[168:169] op_sel_hi:[1,0]
	v_pk_mul_f32 v[122:123], v[122:123], v[168:169] op_sel_hi:[1,0]
	v_pk_mul_f32 v[114:115], v[114:115], v[168:169] op_sel_hi:[1,0]
	v_pk_mul_f32 v[124:125], v[124:125], v[168:169] op_sel_hi:[1,0]
	v_pk_mul_f32 v[116:117], v[116:117], v[168:169] op_sel_hi:[1,0]
	v_pk_mul_f32 v[222:223], v[118:119], v[118:119]
	v_pk_mul_f32 v[224:225], v[120:121], v[120:121]
	v_pk_mul_f32 v[226:227], v[114:115], v[114:115]
	v_pk_mul_f32 v[228:229], v[116:117], v[116:117]
	v_pk_fma_f32 v[222:223], v[126:127], v[126:127], v[222:223]
	v_pk_fma_f32 v[224:225], v[128:129], v[128:129], v[224:225]
	v_pk_fma_f32 v[226:227], v[122:123], v[122:123], v[226:227]
	v_pk_fma_f32 v[228:229], v[124:125], v[124:125], v[228:229]
	v_pk_add_f32 v[222:223], v[222:223], v[224:225]
	v_pk_add_f32 v[226:227], v[226:227], v[228:229]
	s_nop 0
	v_pk_add_f32 v[222:223], v[222:223], v[226:227]
	s_nop 0
	v_add_f32_e32 v222, v222, v223
	s_nop 0
	ds_bpermute_b32 v224, v218, v222
	s_waitcnt lgkmcnt(0)
	v_add_f32_e32 v222, v222, v224
	s_nop 0
	ds_bpermute_b32 v224, v159, v222
	s_waitcnt lgkmcnt(0)
	v_add_f32_e32 v222, v222, v224
	s_nop 0
	v_fmamk_f32 v222, v222, 0x3c800000, v207
	v_rsq_f32_e32 v220, v222
	s_nop 0
	v_pk_mul_f32 v[222:223], v[132:133], v[220:221] op_sel_hi:[1,0]
	v_pk_mul_f32 v[224:225], v[134:135], v[220:221] op_sel_hi:[1,0]
	v_pk_mul_f32 v[226:227], v[136:137], v[220:221] op_sel_hi:[1,0]
	v_pk_mul_f32 v[228:229], v[138:139], v[220:221] op_sel_hi:[1,0]
	v_pk_mul_f32 v[126:127], v[126:127], v[222:223]
	v_pk_mul_f32 v[128:129], v[128:129], v[224:225]
	v_pk_mul_f32 v[122:123], v[122:123], v[226:227]
	v_pk_mul_f32 v[124:125], v[124:125], v[228:229]
	v_pk_mul_f32 v[222:223], v[160:161], v[220:221] op_sel_hi:[1,0]
	v_pk_mul_f32 v[224:225], v[162:163], v[220:221] op_sel_hi:[1,0]
	v_pk_mul_f32 v[226:227], v[164:165], v[220:221] op_sel_hi:[1,0]
	v_pk_mul_f32 v[228:229], v[166:167], v[220:221] op_sel_hi:[1,0]
	v_pk_mul_f32 v[118:119], v[118:119], v[222:223]
	v_pk_mul_f32 v[120:121], v[120:121], v[224:225]
	v_pk_mul_f32 v[114:115], v[114:115], v[226:227]
	v_pk_mul_f32 v[116:117], v[116:117], v[228:229]
	s_waitcnt vmcnt(8)
	v_pk_mul_f32 v[222:223], v[240:241], v[118:119]
	v_pk_mul_f32 v[224:225], v[240:241], v[126:127]
	v_pk_fma_f32 v[118:119], v[232:233], v[118:119], v[224:225]
	v_pk_fma_f32 v[126:127], v[232:233], v[126:127], v[222:223] neg_lo:[0,0,1] neg_hi:[0,0,1]
	v_pk_mul_f32 v[226:227], v[242:243], v[120:121]
	v_pk_mul_f32 v[228:229], v[242:243], v[128:129]
	v_pk_fma_f32 v[120:121], v[234:235], v[120:121], v[228:229]
	v_pk_fma_f32 v[128:129], v[234:235], v[128:129], v[226:227] neg_lo:[0,0,1] neg_hi:[0,0,1]
	v_pk_mul_f32 v[222:223], v[244:245], v[114:115]
	v_pk_mul_f32 v[224:225], v[244:245], v[122:123]
	v_pk_fma_f32 v[114:115], v[236:237], v[114:115], v[224:225]
	v_pk_fma_f32 v[122:123], v[236:237], v[122:123], v[222:223] neg_lo:[0,0,1] neg_hi:[0,0,1]
	v_pk_mul_f32 v[226:227], v[246:247], v[116:117]
	v_pk_mul_f32 v[228:229], v[246:247], v[124:125]
	v_pk_fma_f32 v[116:117], v[238:239], v[116:117], v[228:229]
	v_pk_fma_f32 v[124:125], v[238:239], v[124:125], v[226:227] neg_lo:[0,0,1] neg_hi:[0,0,1]
	s_add_u32 s0, s38, 0x1800
	s_addc_u32 s1, s39, 0
	s_add_u32 s2, s44, 0x1800
	s_addc_u32 s3, s45, 0
	global_load_dwordx4 v[232:235], v130, s[0:1]
	global_load_dwordx4 v[236:239], v130, s[0:1] offset:16
	global_load_dwordx4 v[240:243], v130, s[2:3]
	global_load_dwordx4 v[244:247], v130, s[2:3] offset:16
	v_cvt_pk_bf16_f32 v126, v126, v127
	v_cvt_pk_bf16_f32 v127, v128, v129
	v_cvt_pk_bf16_f32 v128, v122, v123
	v_cvt_pk_bf16_f32 v129, v124, v125
	v_cvt_pk_bf16_f32 v118, v118, v119
	v_cvt_pk_bf16_f32 v119, v120, v121
	v_cvt_pk_bf16_f32 v120, v114, v115
	v_cvt_pk_bf16_f32 v121, v116, v117
	s_mul_i32 s4, s86, 0
	s_add_u32 s4, s82, s4
	s_addc_u32 s5, s83, 0
	global_store_dwordx4 v131, v[126:129], s[4:5]
	global_store_dwordx4 v131, v[118:121], s[4:5] offset:64
	v_pk_mul_f32 v[110:111], v[110:111], v[168:169] op_sel:[0,1]
	v_pk_mul_f32 v[102:103], v[102:103], v[168:169] op_sel:[0,1]
	v_pk_mul_f32 v[112:113], v[112:113], v[168:169] op_sel:[0,1]
	v_pk_mul_f32 v[104:105], v[104:105], v[168:169] op_sel:[0,1]
	v_pk_mul_f32 v[106:107], v[106:107], v[168:169] op_sel:[0,1]
	v_pk_mul_f32 v[98:99], v[98:99], v[168:169] op_sel:[0,1]
	v_pk_mul_f32 v[108:109], v[108:109], v[168:169] op_sel:[0,1]
	v_pk_mul_f32 v[100:101], v[100:101], v[168:169] op_sel:[0,1]
	v_pk_mul_f32 v[222:223], v[102:103], v[102:103]
	v_pk_mul_f32 v[224:225], v[104:105], v[104:105]
	v_pk_mul_f32 v[226:227], v[98:99], v[98:99]
	v_pk_mul_f32 v[228:229], v[100:101], v[100:101]
	v_pk_fma_f32 v[222:223], v[110:111], v[110:111], v[222:223]
	v_pk_fma_f32 v[224:225], v[112:113], v[112:113], v[224:225]
	v_pk_fma_f32 v[226:227], v[106:107], v[106:107], v[226:227]
	v_pk_fma_f32 v[228:229], v[108:109], v[108:109], v[228:229]
	v_pk_add_f32 v[222:223], v[222:223], v[224:225]
	v_pk_add_f32 v[226:227], v[226:227], v[228:229]
	s_nop 0
	v_pk_add_f32 v[222:223], v[222:223], v[226:227]
	s_nop 0
	v_add_f32_e32 v222, v222, v223
	s_nop 0
	ds_bpermute_b32 v224, v218, v222
	s_waitcnt lgkmcnt(0)
	v_add_f32_e32 v222, v222, v224
	s_nop 0
	ds_bpermute_b32 v224, v159, v222
	s_waitcnt lgkmcnt(0)
	v_add_f32_e32 v222, v222, v224
	s_nop 0
	v_fmamk_f32 v222, v222, 0x3c800000, v207
	v_rsq_f32_e32 v220, v222
	s_nop 0
	v_pk_mul_f32 v[222:223], v[132:133], v[220:221] op_sel_hi:[1,0]
	v_pk_mul_f32 v[224:225], v[134:135], v[220:221] op_sel_hi:[1,0]
	v_pk_mul_f32 v[226:227], v[136:137], v[220:221] op_sel_hi:[1,0]
	v_pk_mul_f32 v[228:229], v[138:139], v[220:221] op_sel_hi:[1,0]
	v_pk_mul_f32 v[110:111], v[110:111], v[222:223]
	v_pk_mul_f32 v[112:113], v[112:113], v[224:225]
	v_pk_mul_f32 v[106:107], v[106:107], v[226:227]
	v_pk_mul_f32 v[108:109], v[108:109], v[228:229]
	v_pk_mul_f32 v[222:223], v[160:161], v[220:221] op_sel_hi:[1,0]
	v_pk_mul_f32 v[224:225], v[162:163], v[220:221] op_sel_hi:[1,0]
	v_pk_mul_f32 v[226:227], v[164:165], v[220:221] op_sel_hi:[1,0]
	v_pk_mul_f32 v[228:229], v[166:167], v[220:221] op_sel_hi:[1,0]
	v_pk_mul_f32 v[102:103], v[102:103], v[222:223]
	v_pk_mul_f32 v[104:105], v[104:105], v[224:225]
	v_pk_mul_f32 v[98:99], v[98:99], v[226:227]
	v_pk_mul_f32 v[100:101], v[100:101], v[228:229]
	s_waitcnt vmcnt(10)
	v_pk_mul_f32 v[222:223], v[200:201], v[102:103]
	v_pk_mul_f32 v[224:225], v[200:201], v[110:111]
	v_pk_fma_f32 v[102:103], v[248:249], v[102:103], v[224:225]
	v_pk_fma_f32 v[110:111], v[248:249], v[110:111], v[222:223] neg_lo:[0,0,1] neg_hi:[0,0,1]
	v_pk_mul_f32 v[226:227], v[202:203], v[104:105]
	v_pk_mul_f32 v[228:229], v[202:203], v[112:113]
	v_pk_fma_f32 v[104:105], v[250:251], v[104:105], v[228:229]
	v_pk_fma_f32 v[112:113], v[250:251], v[112:113], v[226:227] neg_lo:[0,0,1] neg_hi:[0,0,1]
	v_pk_mul_f32 v[222:223], v[140:141], v[98:99]
	v_pk_mul_f32 v[224:225], v[140:141], v[106:107]
	v_pk_fma_f32 v[98:99], v[196:197], v[98:99], v[224:225]
	v_pk_fma_f32 v[106:107], v[196:197], v[106:107], v[222:223] neg_lo:[0,0,1] neg_hi:[0,0,1]
	v_pk_mul_f32 v[226:227], v[142:143], v[100:101]
	v_pk_mul_f32 v[228:229], v[142:143], v[108:109]
	v_pk_fma_f32 v[100:101], v[198:199], v[100:101], v[228:229]
	v_pk_fma_f32 v[108:109], v[198:199], v[108:109], v[226:227] neg_lo:[0,0,1] neg_hi:[0,0,1]
	s_add_u32 s0, s38, 0x4000
	s_addc_u32 s1, s39, 0
	s_add_u32 s2, s44, 0x4000
	s_addc_u32 s3, s45, 0
	global_load_dwordx4 v[248:251], v130, s[0:1]
	global_load_dwordx4 v[196:199], v130, s[0:1] offset:16
	global_load_dwordx4 v[200:203], v130, s[2:3]
	global_load_dwordx4 v[140:143], v130, s[2:3] offset:16
	v_cvt_pk_bf16_f32 v110, v110, v111
	v_cvt_pk_bf16_f32 v111, v112, v113
	v_cvt_pk_bf16_f32 v112, v106, v107
	v_cvt_pk_bf16_f32 v113, v108, v109
	v_cvt_pk_bf16_f32 v102, v102, v103
	v_cvt_pk_bf16_f32 v103, v104, v105
	v_cvt_pk_bf16_f32 v104, v98, v99
	v_cvt_pk_bf16_f32 v105, v100, v101
	s_mul_i32 s4, s86, 32
	s_add_u32 s4, s82, s4
	s_addc_u32 s5, s83, 0
	global_store_dwordx4 v131, v[110:113], s[4:5]
	global_store_dwordx4 v131, v[102:105], s[4:5] offset:64
	v_pk_mul_f32 v[94:95], v[94:95], v[170:171] op_sel_hi:[1,0]
	v_pk_mul_f32 v[86:87], v[86:87], v[170:171] op_sel_hi:[1,0]
	v_pk_mul_f32 v[96:97], v[96:97], v[170:171] op_sel_hi:[1,0]
	v_pk_mul_f32 v[88:89], v[88:89], v[170:171] op_sel_hi:[1,0]
	v_pk_mul_f32 v[90:91], v[90:91], v[170:171] op_sel_hi:[1,0]
	v_pk_mul_f32 v[82:83], v[82:83], v[170:171] op_sel_hi:[1,0]
	v_pk_mul_f32 v[92:93], v[92:93], v[170:171] op_sel_hi:[1,0]
	v_pk_mul_f32 v[84:85], v[84:85], v[170:171] op_sel_hi:[1,0]
	v_pk_mul_f32 v[222:223], v[86:87], v[86:87]
	v_pk_mul_f32 v[224:225], v[88:89], v[88:89]
	v_pk_mul_f32 v[226:227], v[82:83], v[82:83]
	v_pk_mul_f32 v[228:229], v[84:85], v[84:85]
	v_pk_fma_f32 v[222:223], v[94:95], v[94:95], v[222:223]
	v_pk_fma_f32 v[224:225], v[96:97], v[96:97], v[224:225]
	v_pk_fma_f32 v[226:227], v[90:91], v[90:91], v[226:227]
	v_pk_fma_f32 v[228:229], v[92:93], v[92:93], v[228:229]
	v_pk_add_f32 v[222:223], v[222:223], v[224:225]
	v_pk_add_f32 v[226:227], v[226:227], v[228:229]
	s_nop 0
	v_pk_add_f32 v[222:223], v[222:223], v[226:227]
	s_nop 0
	v_add_f32_e32 v222, v222, v223
	s_nop 0
	ds_bpermute_b32 v224, v218, v222
	s_waitcnt lgkmcnt(0)
	v_add_f32_e32 v222, v222, v224
	s_nop 0
	ds_bpermute_b32 v224, v159, v222
	s_waitcnt lgkmcnt(0)
	v_add_f32_e32 v222, v222, v224
	s_nop 0
	v_fmamk_f32 v222, v222, 0x3c800000, v207
	v_rsq_f32_e32 v220, v222
	s_nop 0
	v_pk_mul_f32 v[222:223], v[132:133], v[220:221] op_sel_hi:[1,0]
	v_pk_mul_f32 v[224:225], v[134:135], v[220:221] op_sel_hi:[1,0]
	v_pk_mul_f32 v[226:227], v[136:137], v[220:221] op_sel_hi:[1,0]
	v_pk_mul_f32 v[228:229], v[138:139], v[220:221] op_sel_hi:[1,0]
	v_pk_mul_f32 v[94:95], v[94:95], v[222:223]
	v_pk_mul_f32 v[96:97], v[96:97], v[224:225]
	v_pk_mul_f32 v[90:91], v[90:91], v[226:227]
	v_pk_mul_f32 v[92:93], v[92:93], v[228:229]
	v_pk_mul_f32 v[222:223], v[160:161], v[220:221] op_sel_hi:[1,0]
	v_pk_mul_f32 v[224:225], v[162:163], v[220:221] op_sel_hi:[1,0]
	v_pk_mul_f32 v[226:227], v[164:165], v[220:221] op_sel_hi:[1,0]
	v_pk_mul_f32 v[228:229], v[166:167], v[220:221] op_sel_hi:[1,0]
	v_pk_mul_f32 v[86:87], v[86:87], v[222:223]
	v_pk_mul_f32 v[88:89], v[88:89], v[224:225]
	v_pk_mul_f32 v[82:83], v[82:83], v[226:227]
	v_pk_mul_f32 v[84:85], v[84:85], v[228:229]
	s_waitcnt vmcnt(12)
	v_pk_mul_f32 v[222:223], v[188:189], v[86:87]
	v_pk_mul_f32 v[224:225], v[188:189], v[94:95]
	v_pk_fma_f32 v[86:87], v[180:181], v[86:87], v[224:225]
	v_pk_fma_f32 v[94:95], v[180:181], v[94:95], v[222:223] neg_lo:[0,0,1] neg_hi:[0,0,1]
	v_pk_mul_f32 v[226:227], v[190:191], v[88:89]
	v_pk_mul_f32 v[228:229], v[190:191], v[96:97]
	v_pk_fma_f32 v[88:89], v[182:183], v[88:89], v[228:229]
	v_pk_fma_f32 v[96:97], v[182:183], v[96:97], v[226:227] neg_lo:[0,0,1] neg_hi:[0,0,1]
	v_pk_mul_f32 v[222:223], v[192:193], v[82:83]
	v_pk_mul_f32 v[224:225], v[192:193], v[90:91]
	v_pk_fma_f32 v[82:83], v[184:185], v[82:83], v[224:225]
	v_pk_fma_f32 v[90:91], v[184:185], v[90:91], v[222:223] neg_lo:[0,0,1] neg_hi:[0,0,1]
	v_pk_mul_f32 v[226:227], v[194:195], v[84:85]
	v_pk_mul_f32 v[228:229], v[194:195], v[92:93]
	v_pk_fma_f32 v[84:85], v[186:187], v[84:85], v[228:229]
	v_pk_fma_f32 v[92:93], v[186:187], v[92:93], v[226:227] neg_lo:[0,0,1] neg_hi:[0,0,1]
	s_add_u32 s0, s38, 0x4800
	s_addc_u32 s1, s39, 0
	s_add_u32 s2, s44, 0x4800
	s_addc_u32 s3, s45, 0
	global_load_dwordx4 v[180:183], v130, s[0:1]
	global_load_dwordx4 v[184:187], v130, s[0:1] offset:16
	global_load_dwordx4 v[188:191], v130, s[2:3]
	global_load_dwordx4 v[192:195], v130, s[2:3] offset:16
	v_cvt_pk_bf16_f32 v94, v94, v95
	v_cvt_pk_bf16_f32 v95, v96, v97
	v_cvt_pk_bf16_f32 v96, v90, v91
	v_cvt_pk_bf16_f32 v97, v92, v93
	v_cvt_pk_bf16_f32 v86, v86, v87
	v_cvt_pk_bf16_f32 v87, v88, v89
	v_cvt_pk_bf16_f32 v88, v82, v83
	v_cvt_pk_bf16_f32 v89, v84, v85
	s_mul_i32 s4, s86, 64
	s_add_u32 s4, s82, s4
	s_addc_u32 s5, s83, 0
	global_store_dwordx4 v131, v[94:97], s[4:5]
	global_store_dwordx4 v131, v[86:89], s[4:5] offset:64
	v_pk_mul_f32 v[78:79], v[78:79], v[170:171] op_sel:[0,1]
	v_pk_mul_f32 v[70:71], v[70:71], v[170:171] op_sel:[0,1]
	v_pk_mul_f32 v[80:81], v[80:81], v[170:171] op_sel:[0,1]
	v_pk_mul_f32 v[72:73], v[72:73], v[170:171] op_sel:[0,1]
	v_pk_mul_f32 v[74:75], v[74:75], v[170:171] op_sel:[0,1]
	v_pk_mul_f32 v[66:67], v[66:67], v[170:171] op_sel:[0,1]
	v_pk_mul_f32 v[76:77], v[76:77], v[170:171] op_sel:[0,1]
	v_pk_mul_f32 v[68:69], v[68:69], v[170:171] op_sel:[0,1]
	v_pk_mul_f32 v[222:223], v[70:71], v[70:71]
	v_pk_mul_f32 v[224:225], v[72:73], v[72:73]
	v_pk_mul_f32 v[226:227], v[66:67], v[66:67]
	v_pk_mul_f32 v[228:229], v[68:69], v[68:69]
	v_pk_fma_f32 v[222:223], v[78:79], v[78:79], v[222:223]
	v_pk_fma_f32 v[224:225], v[80:81], v[80:81], v[224:225]
	v_pk_fma_f32 v[226:227], v[74:75], v[74:75], v[226:227]
	v_pk_fma_f32 v[228:229], v[76:77], v[76:77], v[228:229]
	v_pk_add_f32 v[222:223], v[222:223], v[224:225]
	v_pk_add_f32 v[226:227], v[226:227], v[228:229]
	s_nop 0
	v_pk_add_f32 v[222:223], v[222:223], v[226:227]
	s_nop 0
	v_add_f32_e32 v222, v222, v223
	s_nop 0
	ds_bpermute_b32 v224, v218, v222
	s_waitcnt lgkmcnt(0)
	v_add_f32_e32 v222, v222, v224
	s_nop 0
	ds_bpermute_b32 v224, v159, v222
	s_waitcnt lgkmcnt(0)
	v_add_f32_e32 v222, v222, v224
	s_nop 0
	v_fmamk_f32 v222, v222, 0x3c800000, v207
	v_rsq_f32_e32 v220, v222
	s_nop 0
	v_pk_mul_f32 v[222:223], v[132:133], v[220:221] op_sel_hi:[1,0]
	v_pk_mul_f32 v[224:225], v[134:135], v[220:221] op_sel_hi:[1,0]
	v_pk_mul_f32 v[226:227], v[136:137], v[220:221] op_sel_hi:[1,0]
	v_pk_mul_f32 v[228:229], v[138:139], v[220:221] op_sel_hi:[1,0]
	v_pk_mul_f32 v[78:79], v[78:79], v[222:223]
	v_pk_mul_f32 v[80:81], v[80:81], v[224:225]
	v_pk_mul_f32 v[74:75], v[74:75], v[226:227]
	v_pk_mul_f32 v[76:77], v[76:77], v[228:229]
	v_pk_mul_f32 v[222:223], v[160:161], v[220:221] op_sel_hi:[1,0]
	v_pk_mul_f32 v[224:225], v[162:163], v[220:221] op_sel_hi:[1,0]
	v_pk_mul_f32 v[226:227], v[164:165], v[220:221] op_sel_hi:[1,0]
	v_pk_mul_f32 v[228:229], v[166:167], v[220:221] op_sel_hi:[1,0]
	v_pk_mul_f32 v[70:71], v[70:71], v[222:223]
	v_pk_mul_f32 v[72:73], v[72:73], v[224:225]
	v_pk_mul_f32 v[66:67], v[66:67], v[226:227]
	v_pk_mul_f32 v[68:69], v[68:69], v[228:229]
	s_waitcnt vmcnt(14)
	v_pk_mul_f32 v[222:223], v[240:241], v[70:71]
	v_pk_mul_f32 v[224:225], v[240:241], v[78:79]
	v_pk_fma_f32 v[70:71], v[232:233], v[70:71], v[224:225]
	v_pk_fma_f32 v[78:79], v[232:233], v[78:79], v[222:223] neg_lo:[0,0,1] neg_hi:[0,0,1]
	v_pk_mul_f32 v[226:227], v[242:243], v[72:73]
	v_pk_mul_f32 v[228:229], v[242:243], v[80:81]
	v_pk_fma_f32 v[72:73], v[234:235], v[72:73], v[228:229]
	v_pk_fma_f32 v[80:81], v[234:235], v[80:81], v[226:227] neg_lo:[0,0,1] neg_hi:[0,0,1]
	v_pk_mul_f32 v[222:223], v[244:245], v[66:67]
	v_pk_mul_f32 v[224:225], v[244:245], v[74:75]
	v_pk_fma_f32 v[66:67], v[236:237], v[66:67], v[224:225]
	v_pk_fma_f32 v[74:75], v[236:237], v[74:75], v[222:223] neg_lo:[0,0,1] neg_hi:[0,0,1]
	v_pk_mul_f32 v[226:227], v[246:247], v[68:69]
	v_pk_mul_f32 v[228:229], v[246:247], v[76:77]
	v_pk_fma_f32 v[68:69], v[238:239], v[68:69], v[228:229]
	v_pk_fma_f32 v[76:77], v[238:239], v[76:77], v[226:227] neg_lo:[0,0,1] neg_hi:[0,0,1]
	s_add_u32 s0, s38, 0x5000
	s_addc_u32 s1, s39, 0
	s_add_u32 s2, s44, 0x5000
	s_addc_u32 s3, s45, 0
	global_load_dwordx4 v[232:235], v130, s[0:1]
	global_load_dwordx4 v[236:239], v130, s[0:1] offset:16
	global_load_dwordx4 v[240:243], v130, s[2:3]
	global_load_dwordx4 v[244:247], v130, s[2:3] offset:16
	v_cvt_pk_bf16_f32 v78, v78, v79
	v_cvt_pk_bf16_f32 v79, v80, v81
	v_cvt_pk_bf16_f32 v80, v74, v75
	v_cvt_pk_bf16_f32 v81, v76, v77
	v_cvt_pk_bf16_f32 v70, v70, v71
	v_cvt_pk_bf16_f32 v71, v72, v73
	v_cvt_pk_bf16_f32 v72, v66, v67
	v_cvt_pk_bf16_f32 v73, v68, v69
	s_mul_i32 s4, s86, 96
	s_add_u32 s4, s82, s4
	s_addc_u32 s5, s83, 0
	global_store_dwordx4 v131, v[78:81], s[4:5]
	global_store_dwordx4 v131, v[70:73], s[4:5] offset:64
	v_pk_mul_f32 v[62:63], v[62:63], v[172:173] op_sel_hi:[1,0]
	v_pk_mul_f32 v[54:55], v[54:55], v[172:173] op_sel_hi:[1,0]
	v_pk_mul_f32 v[64:65], v[64:65], v[172:173] op_sel_hi:[1,0]
	v_pk_mul_f32 v[56:57], v[56:57], v[172:173] op_sel_hi:[1,0]
	v_pk_mul_f32 v[58:59], v[58:59], v[172:173] op_sel_hi:[1,0]
	v_pk_mul_f32 v[50:51], v[50:51], v[172:173] op_sel_hi:[1,0]
	v_pk_mul_f32 v[60:61], v[60:61], v[172:173] op_sel_hi:[1,0]
	v_pk_mul_f32 v[52:53], v[52:53], v[172:173] op_sel_hi:[1,0]
	v_pk_mul_f32 v[222:223], v[54:55], v[54:55]
	v_pk_mul_f32 v[224:225], v[56:57], v[56:57]
	v_pk_mul_f32 v[226:227], v[50:51], v[50:51]
	v_pk_mul_f32 v[228:229], v[52:53], v[52:53]
	v_pk_fma_f32 v[222:223], v[62:63], v[62:63], v[222:223]
	v_pk_fma_f32 v[224:225], v[64:65], v[64:65], v[224:225]
	v_pk_fma_f32 v[226:227], v[58:59], v[58:59], v[226:227]
	v_pk_fma_f32 v[228:229], v[60:61], v[60:61], v[228:229]
	v_pk_add_f32 v[222:223], v[222:223], v[224:225]
	v_pk_add_f32 v[226:227], v[226:227], v[228:229]
	s_nop 0
	v_pk_add_f32 v[222:223], v[222:223], v[226:227]
	s_nop 0
	v_add_f32_e32 v222, v222, v223
	s_nop 0
	ds_bpermute_b32 v224, v218, v222
	s_waitcnt lgkmcnt(0)
	v_add_f32_e32 v222, v222, v224
	s_nop 0
	ds_bpermute_b32 v224, v159, v222
	s_waitcnt lgkmcnt(0)
	v_add_f32_e32 v222, v222, v224
	s_nop 0
	v_fmamk_f32 v222, v222, 0x3c800000, v207
	v_rsq_f32_e32 v220, v222
	s_nop 0
	v_pk_mul_f32 v[222:223], v[132:133], v[220:221] op_sel_hi:[1,0]
	v_pk_mul_f32 v[224:225], v[134:135], v[220:221] op_sel_hi:[1,0]
	v_pk_mul_f32 v[226:227], v[136:137], v[220:221] op_sel_hi:[1,0]
	v_pk_mul_f32 v[228:229], v[138:139], v[220:221] op_sel_hi:[1,0]
	v_pk_mul_f32 v[62:63], v[62:63], v[222:223]
	v_pk_mul_f32 v[64:65], v[64:65], v[224:225]
	v_pk_mul_f32 v[58:59], v[58:59], v[226:227]
	v_pk_mul_f32 v[60:61], v[60:61], v[228:229]
	v_pk_mul_f32 v[222:223], v[160:161], v[220:221] op_sel_hi:[1,0]
	v_pk_mul_f32 v[224:225], v[162:163], v[220:221] op_sel_hi:[1,0]
	v_pk_mul_f32 v[226:227], v[164:165], v[220:221] op_sel_hi:[1,0]
	v_pk_mul_f32 v[228:229], v[166:167], v[220:221] op_sel_hi:[1,0]
	v_pk_mul_f32 v[54:55], v[54:55], v[222:223]
	v_pk_mul_f32 v[56:57], v[56:57], v[224:225]
	v_pk_mul_f32 v[50:51], v[50:51], v[226:227]
	v_pk_mul_f32 v[52:53], v[52:53], v[228:229]
	s_waitcnt vmcnt(14)
	v_pk_mul_f32 v[222:223], v[200:201], v[54:55]
	v_pk_mul_f32 v[224:225], v[200:201], v[62:63]
	v_pk_fma_f32 v[54:55], v[248:249], v[54:55], v[224:225]
	v_pk_fma_f32 v[62:63], v[248:249], v[62:63], v[222:223] neg_lo:[0,0,1] neg_hi:[0,0,1]
	v_pk_mul_f32 v[226:227], v[202:203], v[56:57]
	v_pk_mul_f32 v[228:229], v[202:203], v[64:65]
	v_pk_fma_f32 v[56:57], v[250:251], v[56:57], v[228:229]
	v_pk_fma_f32 v[64:65], v[250:251], v[64:65], v[226:227] neg_lo:[0,0,1] neg_hi:[0,0,1]
	v_pk_mul_f32 v[222:223], v[140:141], v[50:51]
	v_pk_mul_f32 v[224:225], v[140:141], v[58:59]
	v_pk_fma_f32 v[50:51], v[196:197], v[50:51], v[224:225]
	v_pk_fma_f32 v[58:59], v[196:197], v[58:59], v[222:223] neg_lo:[0,0,1] neg_hi:[0,0,1]
	v_pk_mul_f32 v[226:227], v[142:143], v[52:53]
	v_pk_mul_f32 v[228:229], v[142:143], v[60:61]
	v_pk_fma_f32 v[52:53], v[198:199], v[52:53], v[228:229]
	v_pk_fma_f32 v[60:61], v[198:199], v[60:61], v[226:227] neg_lo:[0,0,1] neg_hi:[0,0,1]
	s_add_u32 s0, s38, 0x5800
	s_addc_u32 s1, s39, 0
	s_add_u32 s2, s44, 0x5800
	s_addc_u32 s3, s45, 0
	global_load_dwordx4 v[248:251], v130, s[0:1]
	global_load_dwordx4 v[196:199], v130, s[0:1] offset:16
	global_load_dwordx4 v[200:203], v130, s[2:3]
	global_load_dwordx4 v[140:143], v130, s[2:3] offset:16
	v_cvt_pk_bf16_f32 v62, v62, v63
	v_cvt_pk_bf16_f32 v63, v64, v65
	v_cvt_pk_bf16_f32 v64, v58, v59
	v_cvt_pk_bf16_f32 v65, v60, v61
	v_cvt_pk_bf16_f32 v54, v54, v55
	v_cvt_pk_bf16_f32 v55, v56, v57
	v_cvt_pk_bf16_f32 v56, v50, v51
	v_cvt_pk_bf16_f32 v57, v52, v53
	s_mul_i32 s4, s86, 256
	s_add_u32 s4, s82, s4
	s_addc_u32 s5, s83, 0
	global_store_dwordx4 v131, v[62:65], s[4:5]
	global_store_dwordx4 v131, v[54:57], s[4:5] offset:64
	v_pk_mul_f32 v[46:47], v[46:47], v[172:173] op_sel:[0,1]
	v_pk_mul_f32 v[38:39], v[38:39], v[172:173] op_sel:[0,1]
	v_pk_mul_f32 v[48:49], v[48:49], v[172:173] op_sel:[0,1]
	v_pk_mul_f32 v[40:41], v[40:41], v[172:173] op_sel:[0,1]
	v_pk_mul_f32 v[42:43], v[42:43], v[172:173] op_sel:[0,1]
	v_pk_mul_f32 v[34:35], v[34:35], v[172:173] op_sel:[0,1]
	v_pk_mul_f32 v[44:45], v[44:45], v[172:173] op_sel:[0,1]
	v_pk_mul_f32 v[36:37], v[36:37], v[172:173] op_sel:[0,1]
	v_pk_mul_f32 v[222:223], v[38:39], v[38:39]
	v_pk_mul_f32 v[224:225], v[40:41], v[40:41]
	v_pk_mul_f32 v[226:227], v[34:35], v[34:35]
	v_pk_mul_f32 v[228:229], v[36:37], v[36:37]
	v_pk_fma_f32 v[222:223], v[46:47], v[46:47], v[222:223]
	v_pk_fma_f32 v[224:225], v[48:49], v[48:49], v[224:225]
	v_pk_fma_f32 v[226:227], v[42:43], v[42:43], v[226:227]
	v_pk_fma_f32 v[228:229], v[44:45], v[44:45], v[228:229]
	v_pk_add_f32 v[222:223], v[222:223], v[224:225]
	v_pk_add_f32 v[226:227], v[226:227], v[228:229]
	s_nop 0
	v_pk_add_f32 v[222:223], v[222:223], v[226:227]
	s_nop 0
	v_add_f32_e32 v222, v222, v223
	s_nop 0
	ds_bpermute_b32 v224, v218, v222
	s_waitcnt lgkmcnt(0)
	v_add_f32_e32 v222, v222, v224
	s_nop 0
	ds_bpermute_b32 v224, v159, v222
	s_waitcnt lgkmcnt(0)
	v_add_f32_e32 v222, v222, v224
	s_nop 0
	v_fmamk_f32 v222, v222, 0x3c800000, v207
	v_rsq_f32_e32 v220, v222
	s_nop 0
	v_pk_mul_f32 v[222:223], v[132:133], v[220:221] op_sel_hi:[1,0]
	v_pk_mul_f32 v[224:225], v[134:135], v[220:221] op_sel_hi:[1,0]
	v_pk_mul_f32 v[226:227], v[136:137], v[220:221] op_sel_hi:[1,0]
	v_pk_mul_f32 v[228:229], v[138:139], v[220:221] op_sel_hi:[1,0]
	v_pk_mul_f32 v[46:47], v[46:47], v[222:223]
	v_pk_mul_f32 v[48:49], v[48:49], v[224:225]
	v_pk_mul_f32 v[42:43], v[42:43], v[226:227]
	v_pk_mul_f32 v[44:45], v[44:45], v[228:229]
	v_pk_mul_f32 v[222:223], v[160:161], v[220:221] op_sel_hi:[1,0]
	v_pk_mul_f32 v[224:225], v[162:163], v[220:221] op_sel_hi:[1,0]
	v_pk_mul_f32 v[226:227], v[164:165], v[220:221] op_sel_hi:[1,0]
	v_pk_mul_f32 v[228:229], v[166:167], v[220:221] op_sel_hi:[1,0]
	v_pk_mul_f32 v[38:39], v[38:39], v[222:223]
	v_pk_mul_f32 v[40:41], v[40:41], v[224:225]
	v_pk_mul_f32 v[34:35], v[34:35], v[226:227]
	v_pk_mul_f32 v[36:37], v[36:37], v[228:229]
	s_waitcnt vmcnt(14)
	v_pk_mul_f32 v[222:223], v[188:189], v[38:39]
	v_pk_mul_f32 v[224:225], v[188:189], v[46:47]
	v_pk_fma_f32 v[38:39], v[180:181], v[38:39], v[224:225]
	v_pk_fma_f32 v[46:47], v[180:181], v[46:47], v[222:223] neg_lo:[0,0,1] neg_hi:[0,0,1]
	v_pk_mul_f32 v[226:227], v[190:191], v[40:41]
	v_pk_mul_f32 v[228:229], v[190:191], v[48:49]
	v_pk_fma_f32 v[40:41], v[182:183], v[40:41], v[228:229]
	v_pk_fma_f32 v[48:49], v[182:183], v[48:49], v[226:227] neg_lo:[0,0,1] neg_hi:[0,0,1]
	v_pk_mul_f32 v[222:223], v[192:193], v[34:35]
	v_pk_mul_f32 v[224:225], v[192:193], v[42:43]
	v_pk_fma_f32 v[34:35], v[184:185], v[34:35], v[224:225]
	v_pk_fma_f32 v[42:43], v[184:185], v[42:43], v[222:223] neg_lo:[0,0,1] neg_hi:[0,0,1]
	v_pk_mul_f32 v[226:227], v[194:195], v[36:37]
	v_pk_mul_f32 v[228:229], v[194:195], v[44:45]
	v_pk_fma_f32 v[36:37], v[186:187], v[36:37], v[228:229]
	v_pk_fma_f32 v[44:45], v[186:187], v[44:45], v[226:227] neg_lo:[0,0,1] neg_hi:[0,0,1]
	v_cvt_pk_bf16_f32 v46, v46, v47
	v_cvt_pk_bf16_f32 v47, v48, v49
	v_cvt_pk_bf16_f32 v48, v42, v43
	v_cvt_pk_bf16_f32 v49, v44, v45
	v_cvt_pk_bf16_f32 v38, v38, v39
	v_cvt_pk_bf16_f32 v39, v40, v41
	v_cvt_pk_bf16_f32 v40, v34, v35
	v_cvt_pk_bf16_f32 v41, v36, v37
	s_mul_i32 s4, s86, 288
	s_add_u32 s4, s82, s4
	s_addc_u32 s5, s83, 0
	global_store_dwordx4 v131, v[46:49], s[4:5]
	global_store_dwordx4 v131, v[38:41], s[4:5] offset:64
	v_pk_mul_f32 v[30:31], v[30:31], v[174:175] op_sel_hi:[1,0]
	v_pk_mul_f32 v[22:23], v[22:23], v[174:175] op_sel_hi:[1,0]
	v_pk_mul_f32 v[32:33], v[32:33], v[174:175] op_sel_hi:[1,0]
	v_pk_mul_f32 v[24:25], v[24:25], v[174:175] op_sel_hi:[1,0]
	v_pk_mul_f32 v[26:27], v[26:27], v[174:175] op_sel_hi:[1,0]
	v_pk_mul_f32 v[18:19], v[18:19], v[174:175] op_sel_hi:[1,0]
	v_pk_mul_f32 v[28:29], v[28:29], v[174:175] op_sel_hi:[1,0]
	v_pk_mul_f32 v[20:21], v[20:21], v[174:175] op_sel_hi:[1,0]
	v_pk_mul_f32 v[222:223], v[22:23], v[22:23]
	v_pk_mul_f32 v[224:225], v[24:25], v[24:25]
	v_pk_mul_f32 v[226:227], v[18:19], v[18:19]
	v_pk_mul_f32 v[228:229], v[20:21], v[20:21]
	v_pk_fma_f32 v[222:223], v[30:31], v[30:31], v[222:223]
	v_pk_fma_f32 v[224:225], v[32:33], v[32:33], v[224:225]
	v_pk_fma_f32 v[226:227], v[26:27], v[26:27], v[226:227]
	v_pk_fma_f32 v[228:229], v[28:29], v[28:29], v[228:229]
	v_pk_add_f32 v[222:223], v[222:223], v[224:225]
	v_pk_add_f32 v[226:227], v[226:227], v[228:229]
	s_nop 0
	v_pk_add_f32 v[222:223], v[222:223], v[226:227]
	s_nop 0
	v_add_f32_e32 v222, v222, v223
	s_nop 0
	ds_bpermute_b32 v224, v218, v222
	s_waitcnt lgkmcnt(0)
	v_add_f32_e32 v222, v222, v224
	s_nop 0
	ds_bpermute_b32 v224, v159, v222
	s_waitcnt lgkmcnt(0)
	v_add_f32_e32 v222, v222, v224
	s_nop 0
	v_fmamk_f32 v222, v222, 0x3c800000, v207
	v_rsq_f32_e32 v220, v222
	s_nop 0
	v_pk_mul_f32 v[222:223], v[132:133], v[220:221] op_sel_hi:[1,0]
	v_pk_mul_f32 v[224:225], v[134:135], v[220:221] op_sel_hi:[1,0]
	v_pk_mul_f32 v[226:227], v[136:137], v[220:221] op_sel_hi:[1,0]
	v_pk_mul_f32 v[228:229], v[138:139], v[220:221] op_sel_hi:[1,0]
	v_pk_mul_f32 v[30:31], v[30:31], v[222:223]
	v_pk_mul_f32 v[32:33], v[32:33], v[224:225]
	v_pk_mul_f32 v[26:27], v[26:27], v[226:227]
	v_pk_mul_f32 v[28:29], v[28:29], v[228:229]
	v_pk_mul_f32 v[222:223], v[160:161], v[220:221] op_sel_hi:[1,0]
	v_pk_mul_f32 v[224:225], v[162:163], v[220:221] op_sel_hi:[1,0]
	v_pk_mul_f32 v[226:227], v[164:165], v[220:221] op_sel_hi:[1,0]
	v_pk_mul_f32 v[228:229], v[166:167], v[220:221] op_sel_hi:[1,0]
	v_pk_mul_f32 v[22:23], v[22:23], v[222:223]
	v_pk_mul_f32 v[24:25], v[24:25], v[224:225]
	v_pk_mul_f32 v[18:19], v[18:19], v[226:227]
	v_pk_mul_f32 v[20:21], v[20:21], v[228:229]
	s_waitcnt vmcnt(10)
	v_pk_mul_f32 v[222:223], v[240:241], v[22:23]
	v_pk_mul_f32 v[224:225], v[240:241], v[30:31]
	v_pk_fma_f32 v[22:23], v[232:233], v[22:23], v[224:225]
	v_pk_fma_f32 v[30:31], v[232:233], v[30:31], v[222:223] neg_lo:[0,0,1] neg_hi:[0,0,1]
	v_pk_mul_f32 v[226:227], v[242:243], v[24:25]
	v_pk_mul_f32 v[228:229], v[242:243], v[32:33]
	v_pk_fma_f32 v[24:25], v[234:235], v[24:25], v[228:229]
	v_pk_fma_f32 v[32:33], v[234:235], v[32:33], v[226:227] neg_lo:[0,0,1] neg_hi:[0,0,1]
	v_pk_mul_f32 v[222:223], v[244:245], v[18:19]
	v_pk_mul_f32 v[224:225], v[244:245], v[26:27]
	v_pk_fma_f32 v[18:19], v[236:237], v[18:19], v[224:225]
	v_pk_fma_f32 v[26:27], v[236:237], v[26:27], v[222:223] neg_lo:[0,0,1] neg_hi:[0,0,1]
	v_pk_mul_f32 v[226:227], v[246:247], v[20:21]
	v_pk_mul_f32 v[228:229], v[246:247], v[28:29]
	v_pk_fma_f32 v[20:21], v[238:239], v[20:21], v[228:229]
	v_pk_fma_f32 v[28:29], v[238:239], v[28:29], v[226:227] neg_lo:[0,0,1] neg_hi:[0,0,1]
	v_cvt_pk_bf16_f32 v30, v30, v31
	v_cvt_pk_bf16_f32 v31, v32, v33
	v_cvt_pk_bf16_f32 v32, v26, v27
	v_cvt_pk_bf16_f32 v33, v28, v29
	v_cvt_pk_bf16_f32 v22, v22, v23
	v_cvt_pk_bf16_f32 v23, v24, v25
	v_cvt_pk_bf16_f32 v24, v18, v19
	v_cvt_pk_bf16_f32 v25, v20, v21
	s_mul_i32 s4, s86, 320
	s_add_u32 s4, s82, s4
	s_addc_u32 s5, s83, 0
	global_store_dwordx4 v131, v[30:33], s[4:5]
	global_store_dwordx4 v131, v[22:25], s[4:5] offset:64
	v_pk_mul_f32 v[14:15], v[14:15], v[174:175] op_sel:[0,1]
	v_pk_mul_f32 v[6:7], v[6:7], v[174:175] op_sel:[0,1]
	v_pk_mul_f32 v[16:17], v[16:17], v[174:175] op_sel:[0,1]
	v_pk_mul_f32 v[8:9], v[8:9], v[174:175] op_sel:[0,1]
	v_pk_mul_f32 v[10:11], v[10:11], v[174:175] op_sel:[0,1]
	v_pk_mul_f32 v[2:3], v[2:3], v[174:175] op_sel:[0,1]
	v_pk_mul_f32 v[12:13], v[12:13], v[174:175] op_sel:[0,1]
	v_pk_mul_f32 v[4:5], v[4:5], v[174:175] op_sel:[0,1]
	v_pk_mul_f32 v[222:223], v[6:7], v[6:7]
	v_pk_mul_f32 v[224:225], v[8:9], v[8:9]
	v_pk_mul_f32 v[226:227], v[2:3], v[2:3]
	v_pk_mul_f32 v[228:229], v[4:5], v[4:5]
	v_pk_fma_f32 v[222:223], v[14:15], v[14:15], v[222:223]
	v_pk_fma_f32 v[224:225], v[16:17], v[16:17], v[224:225]
	v_pk_fma_f32 v[226:227], v[10:11], v[10:11], v[226:227]
	v_pk_fma_f32 v[228:229], v[12:13], v[12:13], v[228:229]
	v_pk_add_f32 v[222:223], v[222:223], v[224:225]
	v_pk_add_f32 v[226:227], v[226:227], v[228:229]
	s_nop 0
	v_pk_add_f32 v[222:223], v[222:223], v[226:227]
	s_nop 0
	v_add_f32_e32 v222, v222, v223
	s_nop 0
	ds_bpermute_b32 v224, v218, v222
	s_waitcnt lgkmcnt(0)
	v_add_f32_e32 v222, v222, v224
	s_nop 0
	ds_bpermute_b32 v224, v159, v222
	s_waitcnt lgkmcnt(0)
	v_add_f32_e32 v222, v222, v224
	s_nop 0
	v_fmamk_f32 v222, v222, 0x3c800000, v207
	v_rsq_f32_e32 v220, v222
	s_nop 0
	v_pk_mul_f32 v[222:223], v[132:133], v[220:221] op_sel_hi:[1,0]
	v_pk_mul_f32 v[224:225], v[134:135], v[220:221] op_sel_hi:[1,0]
	v_pk_mul_f32 v[226:227], v[136:137], v[220:221] op_sel_hi:[1,0]
	v_pk_mul_f32 v[228:229], v[138:139], v[220:221] op_sel_hi:[1,0]
	v_pk_mul_f32 v[14:15], v[14:15], v[222:223]
	v_pk_mul_f32 v[16:17], v[16:17], v[224:225]
	v_pk_mul_f32 v[10:11], v[10:11], v[226:227]
	v_pk_mul_f32 v[12:13], v[12:13], v[228:229]
	v_pk_mul_f32 v[222:223], v[160:161], v[220:221] op_sel_hi:[1,0]
	v_pk_mul_f32 v[224:225], v[162:163], v[220:221] op_sel_hi:[1,0]
	v_pk_mul_f32 v[226:227], v[164:165], v[220:221] op_sel_hi:[1,0]
	v_pk_mul_f32 v[228:229], v[166:167], v[220:221] op_sel_hi:[1,0]
	v_pk_mul_f32 v[6:7], v[6:7], v[222:223]
	v_pk_mul_f32 v[8:9], v[8:9], v[224:225]
	v_pk_mul_f32 v[2:3], v[2:3], v[226:227]
	v_pk_mul_f32 v[4:5], v[4:5], v[228:229]
	s_waitcnt vmcnt(6)
	v_pk_mul_f32 v[222:223], v[200:201], v[6:7]
	v_pk_mul_f32 v[224:225], v[200:201], v[14:15]
	v_pk_fma_f32 v[6:7], v[248:249], v[6:7], v[224:225]
	v_pk_fma_f32 v[14:15], v[248:249], v[14:15], v[222:223] neg_lo:[0,0,1] neg_hi:[0,0,1]
	v_pk_mul_f32 v[226:227], v[202:203], v[8:9]
	v_pk_mul_f32 v[228:229], v[202:203], v[16:17]
	v_pk_fma_f32 v[8:9], v[250:251], v[8:9], v[228:229]
	v_pk_fma_f32 v[16:17], v[250:251], v[16:17], v[226:227] neg_lo:[0,0,1] neg_hi:[0,0,1]
	v_pk_mul_f32 v[222:223], v[140:141], v[2:3]
	v_pk_mul_f32 v[224:225], v[140:141], v[10:11]
	v_pk_fma_f32 v[2:3], v[196:197], v[2:3], v[224:225]
	v_pk_fma_f32 v[10:11], v[196:197], v[10:11], v[222:223] neg_lo:[0,0,1] neg_hi:[0,0,1]
	v_pk_mul_f32 v[226:227], v[142:143], v[4:5]
	v_pk_mul_f32 v[228:229], v[142:143], v[12:13]
	v_pk_fma_f32 v[4:5], v[198:199], v[4:5], v[228:229]
	v_pk_fma_f32 v[12:13], v[198:199], v[12:13], v[226:227] neg_lo:[0,0,1] neg_hi:[0,0,1]
	v_cvt_pk_bf16_f32 v14, v14, v15
	v_cvt_pk_bf16_f32 v15, v16, v17
	v_cvt_pk_bf16_f32 v16, v10, v11
	v_cvt_pk_bf16_f32 v17, v12, v13
	v_cvt_pk_bf16_f32 v6, v6, v7
	v_cvt_pk_bf16_f32 v7, v8, v9
	v_cvt_pk_bf16_f32 v8, v2, v3
	v_cvt_pk_bf16_f32 v9, v4, v5
	s_mul_i32 s4, s86, 352
	s_add_u32 s4, s82, s4
	s_addc_u32 s5, s83, 0
	global_store_dwordx4 v131, v[14:17], s[4:5]
	global_store_dwordx4 v131, v[6:9], s[4:5] offset:64
	s_mov_b64 s[0:1], 0
